# phase 11a token loop rewritten by hand: one gelu+scale+store sequence per token over all pair groups, SALU token addressing, saddr gathers
# speedup vs baseline: 1.0354x; 1.0354x over previous
; DI void phase11a(const Params& P, char* smem_all) {
;     ...
;   const int j = RBLK & 7, lane = RTID & 63, wslot = (RBLK >> 3) * 8 + (RTID >> 6), nw = (RGRID >> 3) * 8;
;   const int l16 = lane & 15, rg = lane >> 4;
;   uint2* lst = (uint2*)(smem_all + (RTID >> 6) * 1024);
;   int nE0 = Eidx[(long)wslot * 128 + lane], nE1 = Eidx[(long)wslot * 128 + 64 + lane];
;   float nG0 = G[(long)wslot * 128 + lane], nG1 = G[(long)wslot * 128 + 64 + lane];
;   uint4 nx[4];
; #pragma unroll
;   for (int c = 0; c < 4; ++c) nx[c] = *reinterpret_cast<const uint4*>(xq + (long)wslot * 1024 + (c * 16 + l16) * 16);
;   float nsx = sxp[wslot];
;   for (int t = wslot; t < NTOK; t += nw) {
;     const int E0 = nE0, E1 = nE1; const float G0 = nG0, G1 = nG1, sx = nsx;
;     uint4 xr[4];
; #pragma unroll
;     for (int c = 0; c < 4; ++c) xr[c] = nx[c];
;     bool pf = false;
;     const int tn = t + nw < NTOK ? t + nw : t;
;     if (j == 0) { E2[(long)t * 128 + (lane & 7) * 16 + (lane >> 3)] = E0; E2[(long)t * 128 + (lane & 7) * 16 + 8 + (lane >> 3)] = E1; }
;     const bool in0 = (E0 >> 11) == j, in1 = (E1 >> 11) == j;
;     const unsigned long long m0 = __ballot(in0), m1 = __ballot(in1);
;     const int c0 = __popcll(m0), cnt = c0 + __popcll(m1);
;     const int r0 = __builtin_amdgcn_mbcnt_hi((unsigned)(m0 >> 32), __builtin_amdgcn_mbcnt_lo((unsigned)m0, 0u));
;     const int r1 = c0 + __builtin_amdgcn_mbcnt_hi((unsigned)(m1 >> 32), __builtin_amdgcn_mbcnt_lo((unsigned)m1, 0u));
;     if (in0) lst[r0] = make_uint2((unsigned)E0 | ((unsigned)lane << 14), __float_as_uint(G0));
;     if (in1) lst[r1] = make_uint2((unsigned)E1 | ((unsigned)(64 + lane) << 14), __float_as_uint(G1));
;     for (int g0 = 0; g0 < cnt; g0 += 24) {
;       const int rem = cnt - g0, ng = rem >= 24 ? 6 : (rem + 3) >> 2;
;       int el[6], pl[6]; float gl[6];
; #pragma unroll
;       for (int gi = 0; gi < 6; ++gi) {
;         const int idx = g0 + 4 * gi + rg; const bool ok = idx < cnt;
;         const uint2 en = lst[ok ? idx : 0];
;         el[gi] = ok ? (int)(en.x & 16383u) : 0; pl[gi] = ok ? (int)(en.x >> 14) : -1; gl[gi] = ok ? __uint_as_float(en.y) : 0.f;
;       }
;       uint4 u[6][4]; float su[6], sv[6];
; #pragma unroll
;       for (int gi = 0; gi < 6; ++gi) {
;         if (gi < ng) {
;           const char* rowp = Uq + (long)el[gi] * 1024 + l16 * 16;
; #pragma unroll
.LBB0_1441:
	s_or_b64 exec, exec, s[0:1]
	s_add_u32 s24, s78, 0x1b200000
	s_addc_u32 s25, s79, 0
	s_and_b32 s0, s22, -8
	v_add_u32_e32 v212, s0, v172
	s_and_b32 s5, s22, 7
	s_mov_b32 s22, 0x8000
	s_and_b32 s4, s64, -8
	v_cmp_gt_i32_e64 s[2:3], s22, v212
	v_ashrrev_i32_e32 v213, 31, v212
	s_waitcnt lgkmcnt(0)
	s_barrier
	s_and_saveexec_b64 s[26:27], s[2:3]
	s_cbranch_execz .LBB0_1525
	s_add_u32 s28, s78, 0x2100000
	s_addc_u32 s29, s79, 0
	s_add_u32 s32, s78, 0x2000000
	s_addc_u32 s33, s79, 0
	s_add_u32 s30, s78, 0x1b000000
	s_addc_u32 s31, s79, 0
	s_add_u32 s34, s78, 0x1c200000
	s_addc_u32 s35, s79, 0
	s_mov_b32 s19, 0xfffc00
	v_lshlrev_b32_e32 v0, 2, v208
	v_and_b32_e32 v2, 15, v208
	v_lshrrev_b32_e32 v3, 4, v208
	v_lshlrev_b32_e32 v1, 4, v2
	v_and_b32_e32 v4, 0x3c00, v209
	v_lshlrev_b32_e32 v5, 3, v208
	v_add_u32_e32 v5, 0x2000, v5
	v_lshl_add_u32 v157, v2, 2, v3
	v_add_u32_e32 v166, 64, v208
	v_and_b32_e32 v158, 7, v208
	v_lshlrev_b32_e32 v158, 6, v158
	v_lshrrev_b32_e32 v159, 3, v208
	v_lshl_or_b32 v158, v159, 2, v158
	v_add_u32_e32 v159, 32, v158
	v_cmp_eq_u32_e64 s[80:81], 0, v2
	v_cmp_eq_u32_e64 s[82:83], 1, v2
	v_cmp_eq_u32_e64 s[84:85], 2, v2
	v_cmp_eq_u32_e64 s[86:87], 3, v2
	v_cmp_eq_u32_e64 s[88:89], 4, v2
	v_cmp_eq_u32_e64 s[90:91], 5, v2
	v_cmp_gt_u32_e64 s[94:95], 6, v2
	v_readfirstlane_b32 s6, v212
	s_nop 3
	s_mov_b32 s7, s6
	s_lshl_b32 s0, s7, 9
	s_add_u32 s8, s38, s0
	s_addc_u32 s9, s39, 0
	global_load_dword v10, v0, s[8:9]
	global_load_dword v11, v0, s[8:9] offset:256
	s_add_u32 s8, s42, s0
	s_addc_u32 s9, s43, 0
	global_load_dword v12, v0, s[8:9]
	global_load_dword v13, v0, s[8:9] offset:256
	s_lshl_b32 s0, s7, 10
	s_add_u32 s8, s62, s0
	s_addc_u32 s9, s63, 0
	global_load_dwordx4 v[32:35], v1, s[8:9]
	global_load_dwordx4 v[36:39], v1, s[8:9] offset:256
	global_load_dwordx4 v[40:43], v1, s[8:9] offset:512
	global_load_dwordx4 v[44:47], v1, s[8:9] offset:768
	s_lshl_b32 s0, s7, 2
	s_add_u32 s8, s30, s0
	s_addc_u32 s9, s31, 0
	s_load_dword s15, s[8:9], 0x0
	s_waitcnt vmcnt(0)
.Lp11a_tok:
	s_waitcnt vmcnt(1) lgkmcnt(0)
	v_mov_b32_e32 v6, v10
	v_mov_b32_e32 v7, v11
	v_mov_b32_e32 v8, v12
	v_mov_b32_e32 v9, v13
	v_mov_b64_e32 v[16:17], v[32:33]
	v_mov_b64_e32 v[18:19], v[34:35]
	v_mov_b64_e32 v[20:21], v[36:37]
	v_mov_b64_e32 v[22:23], v[38:39]
	v_mov_b64_e32 v[24:25], v[40:41]
	v_mov_b64_e32 v[26:27], v[42:43]
	v_mov_b64_e32 v[28:29], v[44:45]
	v_mov_b64_e32 v[30:31], v[46:47]
	s_mov_b32 s14, s15
	s_add_i32 s7, s6, s4
	s_cmp_lt_i32 s7, s22
	s_cselect_b32 s7, s7, s6
	s_lshl_b32 s0, s6, 9
	s_add_u32 s36, s24, s0
	s_addc_u32 s37, s25, 0
	s_cmp_lg_u32 s5, 0
	s_cbranch_scc1 .Lp11a_noe2
	s_add_u32 s20, s34, s0
	s_addc_u32 s21, s35, 0
	global_store_dword v158, v6, s[20:21]
	global_store_dword v159, v7, s[20:21]
.Lp11a_noe2:
	v_lshrrev_b32_e32 v160, 11, v6
	v_lshrrev_b32_e32 v161, 11, v7
	v_cmp_eq_u32_e64 s[44:45], s5, v160
	v_cmp_eq_u32_e64 s[46:47], s5, v161
	v_lshl_or_b32 v162, v6, 10, v208
	v_mov_b32_e32 v163, v8
	v_lshl_or_b32 v164, v7, 10, v166
	v_mov_b32_e32 v165, v9
	s_bcnt1_i32_b64 s10, s[44:45]
	s_bcnt1_i32_b64 s11, s[46:47]
	s_add_i32 s11, s11, s10
	v_mbcnt_lo_u32_b32 v160, s44, 0
	v_mbcnt_hi_u32_b32 v160, s45, v160
	v_mbcnt_lo_u32_b32 v161, s46, 0
	v_mbcnt_hi_u32_b32 v161, s47, v161
	v_add_u32_e32 v161, s10, v161
	v_lshl_add_u32 v160, v160, 3, v4
	v_lshl_add_u32 v161, v161, 3, v4
	v_cndmask_b32_e64 v160, v5, v160, s[44:45]
	v_cndmask_b32_e64 v161, v5, v161, s[46:47]
	ds_write_b64 v160, v[162:163]
	ds_write_b64 v161, v[164:165]
	s_cmp_eq_u32 s11, 0
	s_cbranch_scc1 .Lp11a_empty
	s_add_i32 s18, s11, -1
	s_mov_b32 s12, 0
	s_waitcnt lgkmcnt(0)
.Lp11a_chunk:
	s_sub_i32 s13, s11, s12
	s_add_i32 s13, s13, 3
	s_lshr_b32 s13, s13, 2
	s_min_u32 s13, s13, 6
	v_add_u32_e32 v167, s12, v157
	v_cmp_gt_u32_e64 s[16:17], s11, v167
	v_min_u32_e32 v168, s18, v167
	v_lshl_add_u32 v168, v168, 3, v4
	ds_read_b64 v[154:155], v168
	v_add_u32_e32 v169, s12, v3
	v_lshl_add_u32 v169, v169, 3, v4
	ds_read2_b32 v[144:145], v169 offset1:8
	ds_read2_b32 v[146:147], v169 offset0:16 offset1:24
	ds_read2_b32 v[148:149], v169 offset0:32 offset1:40
	s_and_b64 s[16:17], s[16:17], s[94:95]
	s_waitcnt lgkmcnt(0)
	v_and_or_b32 v160, v144, s19, v1
	global_load_dwordx4 v[48:51], v160, s[78:79]
	global_load_dwordx4 v[52:55], v160, s[78:79] offset:256
	global_load_dwordx4 v[56:59], v160, s[78:79] offset:512
	global_load_dwordx4 v[60:63], v160, s[78:79] offset:768
	s_cmp_lt_u32 s13, 2
	s_cbranch_scc1 .Lp11a_issued
	v_and_or_b32 v161, v145, s19, v1
	global_load_dwordx4 v[64:67], v161, s[78:79]
	global_load_dwordx4 v[68:71], v161, s[78:79] offset:256
	global_load_dwordx4 v[72:75], v161, s[78:79] offset:512
	global_load_dwordx4 v[76:79], v161, s[78:79] offset:768
	s_cmp_lt_u32 s13, 3
	s_cbranch_scc1 .Lp11a_issued
	v_and_or_b32 v160, v146, s19, v1
	global_load_dwordx4 v[80:83], v160, s[78:79]
	global_load_dwordx4 v[84:87], v160, s[78:79] offset:256
	global_load_dwordx4 v[88:91], v160, s[78:79] offset:512
	global_load_dwordx4 v[92:95], v160, s[78:79] offset:768
	s_cmp_lt_u32 s13, 4
	s_cbranch_scc1 .Lp11a_issued
	v_and_or_b32 v161, v147, s19, v1
	global_load_dwordx4 v[96:99], v161, s[78:79]
	global_load_dwordx4 v[100:103], v161, s[78:79] offset:256
	global_load_dwordx4 v[104:107], v161, s[78:79] offset:512
	global_load_dwordx4 v[108:111], v161, s[78:79] offset:768
	s_cmp_lt_u32 s13, 5
	s_cbranch_scc1 .Lp11a_issued
	v_and_or_b32 v160, v148, s19, v1
	global_load_dwordx4 v[112:115], v160, s[78:79]
	global_load_dwordx4 v[116:119], v160, s[78:79] offset:256
	global_load_dwordx4 v[120:123], v160, s[78:79] offset:512
	global_load_dwordx4 v[124:127], v160, s[78:79] offset:768
	s_cmp_lt_u32 s13, 6
	s_cbranch_scc1 .Lp11a_issued
	v_and_or_b32 v161, v149, s19, v1
	global_load_dwordx4 v[128:131], v161, s[78:79]
	global_load_dwordx4 v[132:135], v161, s[78:79] offset:256
	global_load_dwordx4 v[136:139], v161, s[78:79] offset:512
	global_load_dwordx4 v[140:143], v161, s[78:79] offset:768
.Lp11a_issued:
	v_lshrrev_b32_e32 v175, 8, v154
	v_and_b32_e32 v175, 0xfffc, v175
	global_load_dword v156, v175, s[32:33]
	global_load_dword v153, v175, s[28:29]
	s_cmp_lg_u32 s12, 0
	s_cbranch_scc1 .Lp11a_later
	s_lshl_b32 s0, s7, 9
	s_add_u32 s8, s38, s0
	s_addc_u32 s9, s39, 0
	global_load_dword v10, v0, s[8:9]
	global_load_dword v11, v0, s[8:9] offset:256
	s_add_u32 s8, s42, s0
	s_addc_u32 s9, s43, 0
	global_load_dword v12, v0, s[8:9]
	global_load_dword v13, v0, s[8:9] offset:256
	s_lshl_b32 s0, s7, 10
	s_add_u32 s8, s62, s0
	s_addc_u32 s9, s63, 0
	global_load_dwordx4 v[32:35], v1, s[8:9]
	global_load_dwordx4 v[36:39], v1, s[8:9] offset:256
	global_load_dwordx4 v[40:43], v1, s[8:9] offset:512
	global_load_dwordx4 v[44:47], v1, s[8:9] offset:768
	s_lshl_b32 s0, s7, 2
	s_add_u32 s8, s30, s0
	s_addc_u32 s9, s31, 0
	s_load_dword s15, s[8:9], 0x0
	s_waitcnt vmcnt(9)
	s_branch .Lp11a_dots

; DI void phase11a(const Params& P, char* smem_all) {
;     ...
; #pragma unroll
;       for (int gi = 0; gi < 6; ++gi) {
;         if (gi < ng) {
;           int d = 0;
; #pragma unroll
;           for (int c = 0; c < 4; ++c) {
;             d = __builtin_amdgcn_sdot4((int)u[gi][c].x, (int)xr[c].x, d, false);
;             d = __builtin_amdgcn_sdot4((int)u[gi][c].y, (int)xr[c].y, d, false);
;             d = __builtin_amdgcn_sdot4((int)u[gi][c].z, (int)xr[c].z, d, false);
;             d = __builtin_amdgcn_sdot4((int)u[gi][c].w, (int)xr[c].w, d, false);
;           }
.Lp11a_dots:
	v_mov_b32_e32 v176, 0
	v_dot4c_i32_i8_e32 v176, v48, v16
	v_dot4c_i32_i8_e32 v176, v49, v17
	v_dot4c_i32_i8_e32 v176, v50, v18
	v_dot4c_i32_i8_e32 v176, v51, v19
	v_dot4c_i32_i8_e32 v176, v52, v20
	v_dot4c_i32_i8_e32 v176, v53, v21
	v_dot4c_i32_i8_e32 v176, v54, v22
	v_dot4c_i32_i8_e32 v176, v55, v23
	v_dot4c_i32_i8_e32 v176, v56, v24
	v_dot4c_i32_i8_e32 v176, v57, v25
	v_dot4c_i32_i8_e32 v176, v58, v26
	v_dot4c_i32_i8_e32 v176, v59, v27
	v_dot4c_i32_i8_e32 v176, v60, v28
	v_dot4c_i32_i8_e32 v176, v61, v29
	v_dot4c_i32_i8_e32 v176, v62, v30
	v_dot4c_i32_i8_e32 v176, v63, v31
	s_cmp_lt_u32 s13, 2
	s_cbranch_scc1 .Lp11a_dotted
	v_mov_b32_e32 v177, 0
	v_dot4c_i32_i8_e32 v177, v64, v16
	v_dot4c_i32_i8_e32 v177, v65, v17
	v_dot4c_i32_i8_e32 v177, v66, v18
	v_dot4c_i32_i8_e32 v177, v67, v19
	v_dot4c_i32_i8_e32 v177, v68, v20
	v_dot4c_i32_i8_e32 v177, v69, v21
	v_dot4c_i32_i8_e32 v177, v70, v22
	v_dot4c_i32_i8_e32 v177, v71, v23
	v_dot4c_i32_i8_e32 v177, v72, v24
	v_dot4c_i32_i8_e32 v177, v73, v25
	v_dot4c_i32_i8_e32 v177, v74, v26
	v_dot4c_i32_i8_e32 v177, v75, v27
	v_dot4c_i32_i8_e32 v177, v76, v28
	v_dot4c_i32_i8_e32 v177, v77, v29
	v_dot4c_i32_i8_e32 v177, v78, v30
	v_dot4c_i32_i8_e32 v177, v79, v31
	s_cmp_lt_u32 s13, 3
	s_cbranch_scc1 .Lp11a_dotted
	v_mov_b32_e32 v178, 0
	v_dot4c_i32_i8_e32 v178, v80, v16
	v_dot4c_i32_i8_e32 v178, v81, v17
	v_dot4c_i32_i8_e32 v178, v82, v18
	v_dot4c_i32_i8_e32 v178, v83, v19
	v_dot4c_i32_i8_e32 v178, v84, v20
	v_dot4c_i32_i8_e32 v178, v85, v21
	v_dot4c_i32_i8_e32 v178, v86, v22
	v_dot4c_i32_i8_e32 v178, v87, v23
	v_dot4c_i32_i8_e32 v178, v88, v24
	v_dot4c_i32_i8_e32 v178, v89, v25
	v_dot4c_i32_i8_e32 v178, v90, v26
	v_dot4c_i32_i8_e32 v178, v91, v27
	v_dot4c_i32_i8_e32 v178, v92, v28
	v_dot4c_i32_i8_e32 v178, v93, v29
	v_dot4c_i32_i8_e32 v178, v94, v30
	v_dot4c_i32_i8_e32 v178, v95, v31
	s_cmp_lt_u32 s13, 4
	s_cbranch_scc1 .Lp11a_dotted
	v_mov_b32_e32 v179, 0
	v_dot4c_i32_i8_e32 v179, v96, v16
	v_dot4c_i32_i8_e32 v179, v97, v17
	v_dot4c_i32_i8_e32 v179, v98, v18
	v_dot4c_i32_i8_e32 v179, v99, v19
	v_dot4c_i32_i8_e32 v179, v100, v20
	v_dot4c_i32_i8_e32 v179, v101, v21
	v_dot4c_i32_i8_e32 v179, v102, v22
	v_dot4c_i32_i8_e32 v179, v103, v23
	v_dot4c_i32_i8_e32 v179, v104, v24
	v_dot4c_i32_i8_e32 v179, v105, v25
	v_dot4c_i32_i8_e32 v179, v106, v26
	v_dot4c_i32_i8_e32 v179, v107, v27
	v_dot4c_i32_i8_e32 v179, v108, v28
	v_dot4c_i32_i8_e32 v179, v109, v29
	v_dot4c_i32_i8_e32 v179, v110, v30
	v_dot4c_i32_i8_e32 v179, v111, v31
	s_cmp_lt_u32 s13, 5
	s_cbranch_scc1 .Lp11a_dotted
	v_mov_b32_e32 v180, 0
	v_dot4c_i32_i8_e32 v180, v112, v16
	v_dot4c_i32_i8_e32 v180, v113, v17
	v_dot4c_i32_i8_e32 v180, v114, v18
	v_dot4c_i32_i8_e32 v180, v115, v19
	v_dot4c_i32_i8_e32 v180, v116, v20
	v_dot4c_i32_i8_e32 v180, v117, v21
	v_dot4c_i32_i8_e32 v180, v118, v22
	v_dot4c_i32_i8_e32 v180, v119, v23
	v_dot4c_i32_i8_e32 v180, v120, v24
	v_dot4c_i32_i8_e32 v180, v121, v25
	v_dot4c_i32_i8_e32 v180, v122, v26
	v_dot4c_i32_i8_e32 v180, v123, v27
	v_dot4c_i32_i8_e32 v180, v124, v28
	v_dot4c_i32_i8_e32 v180, v125, v29
	v_dot4c_i32_i8_e32 v180, v126, v30
	v_dot4c_i32_i8_e32 v180, v127, v31
	s_cmp_lt_u32 s13, 6
	s_cbranch_scc1 .Lp11a_dotted
	v_mov_b32_e32 v181, 0
	v_dot4c_i32_i8_e32 v181, v128, v16
	v_dot4c_i32_i8_e32 v181, v129, v17
	v_dot4c_i32_i8_e32 v181, v130, v18
	v_dot4c_i32_i8_e32 v181, v131, v19
	v_dot4c_i32_i8_e32 v181, v132, v20
	v_dot4c_i32_i8_e32 v181, v133, v21
	v_dot4c_i32_i8_e32 v181, v134, v22
	v_dot4c_i32_i8_e32 v181, v135, v23
	v_dot4c_i32_i8_e32 v181, v136, v24
	v_dot4c_i32_i8_e32 v181, v137, v25
	v_dot4c_i32_i8_e32 v181, v138, v26
	v_dot4c_i32_i8_e32 v181, v139, v27
	v_dot4c_i32_i8_e32 v181, v140, v28
	v_dot4c_i32_i8_e32 v181, v141, v29
	v_dot4c_i32_i8_e32 v181, v142, v30
	v_dot4c_i32_i8_e32 v181, v143, v31
; DI float gelu_t(float x) { float u = 0.7978845608028654f * (x + 0.044715f * x * x * x); float e = __expf(2.f * u); float t = 1.f - 2.f / (1.f + e); return 0.5f * x * (1.f + t); }
; DI void phase11a(const Params& P, char* smem_all) {
;     ...
;           d = dpp_row_sum_i(d);
;           const float dot = (float)d * (su[gi] * sx);
;           const float w = gl[gi] * gelu_t(dot) * sv[gi];
;           const int p = pl[gi];
;           if (l16 == 0 && p >= 0) W2[(long)t * 128 + (p & 7) * 16 + (p >> 3)] = w;
;         }
;       }
;     }
;     if (!pf) {
;       nE0 = Eidx[(long)tn * 128 + lane]; nE1 = Eidx[(long)tn * 128 + 64 + lane];
;       nG0 = G[(long)tn * 128 + lane]; nG1 = G[(long)tn * 128 + 64 + lane];
; #pragma unroll
;       for (int c = 0; c < 4; ++c) nx[c] = *reinterpret_cast<const uint4*>(xq + (long)tn * 1024 + (c * 16 + l16) * 16);
;       nsx = sxp[tn];
;     }
.Lp11a_dotted:
	s_nop 2
	v_add_u32_dpp v176, v176, v176 quad_perm:[1,0,3,2] row_mask:0xf bank_mask:0xf bound_ctrl:1
	v_add_u32_dpp v177, v177, v177 quad_perm:[1,0,3,2] row_mask:0xf bank_mask:0xf bound_ctrl:1
	v_add_u32_dpp v178, v178, v178 quad_perm:[1,0,3,2] row_mask:0xf bank_mask:0xf bound_ctrl:1
	v_add_u32_dpp v179, v179, v179 quad_perm:[1,0,3,2] row_mask:0xf bank_mask:0xf bound_ctrl:1
	v_add_u32_dpp v180, v180, v180 quad_perm:[1,0,3,2] row_mask:0xf bank_mask:0xf bound_ctrl:1
	v_add_u32_dpp v181, v181, v181 quad_perm:[1,0,3,2] row_mask:0xf bank_mask:0xf bound_ctrl:1
	v_add_u32_dpp v176, v176, v176 quad_perm:[2,3,0,1] row_mask:0xf bank_mask:0xf bound_ctrl:1
	v_add_u32_dpp v177, v177, v177 quad_perm:[2,3,0,1] row_mask:0xf bank_mask:0xf bound_ctrl:1
	v_add_u32_dpp v178, v178, v178 quad_perm:[2,3,0,1] row_mask:0xf bank_mask:0xf bound_ctrl:1
	v_add_u32_dpp v179, v179, v179 quad_perm:[2,3,0,1] row_mask:0xf bank_mask:0xf bound_ctrl:1
	v_add_u32_dpp v180, v180, v180 quad_perm:[2,3,0,1] row_mask:0xf bank_mask:0xf bound_ctrl:1
	v_add_u32_dpp v181, v181, v181 quad_perm:[2,3,0,1] row_mask:0xf bank_mask:0xf bound_ctrl:1
	v_add_u32_dpp v176, v176, v176 row_half_mirror row_mask:0xf bank_mask:0xf bound_ctrl:1
	v_add_u32_dpp v177, v177, v177 row_half_mirror row_mask:0xf bank_mask:0xf bound_ctrl:1
	v_add_u32_dpp v178, v178, v178 row_half_mirror row_mask:0xf bank_mask:0xf bound_ctrl:1
	v_add_u32_dpp v179, v179, v179 row_half_mirror row_mask:0xf bank_mask:0xf bound_ctrl:1
	v_add_u32_dpp v180, v180, v180 row_half_mirror row_mask:0xf bank_mask:0xf bound_ctrl:1
	v_add_u32_dpp v181, v181, v181 row_half_mirror row_mask:0xf bank_mask:0xf bound_ctrl:1
	v_add_u32_dpp v176, v176, v176 row_mirror row_mask:0xf bank_mask:0xf bound_ctrl:1
	v_add_u32_dpp v177, v177, v177 row_mirror row_mask:0xf bank_mask:0xf bound_ctrl:1
	v_add_u32_dpp v178, v178, v178 row_mirror row_mask:0xf bank_mask:0xf bound_ctrl:1
	v_add_u32_dpp v179, v179, v179 row_mirror row_mask:0xf bank_mask:0xf bound_ctrl:1
	v_add_u32_dpp v180, v180, v180 row_mirror row_mask:0xf bank_mask:0xf bound_ctrl:1
	v_add_u32_dpp v181, v181, v181 row_mirror row_mask:0xf bank_mask:0xf bound_ctrl:1
	v_cndmask_b32_e64 v152, v176, v177, s[82:83]
	v_cndmask_b32_e64 v152, v152, v178, s[84:85]
	v_cndmask_b32_e64 v152, v152, v179, s[86:87]
	v_cndmask_b32_e64 v152, v152, v180, s[88:89]
	v_cndmask_b32_e64 v152, v152, v181, s[90:91]
	v_cvt_f32_i32_e32 v182, v152
	v_mul_f32_e32 v183, s14, v156
	v_mul_f32_e32 v182, v183, v182
	v_mul_f32_e32 v183, 0x3d372713, v182
	v_mul_f32_e32 v183, v182, v183
	v_mul_f32_e32 v184, 0.5, v182
	v_fmac_f32_e32 v182, v182, v183
	v_mul_f32_e32 v182, 0x3f4c422a, v182
	v_add_f32_e32 v182, v182, v182
	v_mul_f32_e32 v182, 0x3fb8aa3b, v182
	v_exp_f32_e32 v182, v182
	v_and_b32_e32 v190, 0x7f, v154
	v_add_f32_e32 v182, 1.0, v182
	v_div_scale_f32 v185, s[0:1], v182, v182, 2.0
	v_rcp_f32_e32 v186, v185
	v_div_scale_f32 v187, vcc, 2.0, v182, 2.0
	v_fma_f32 v188, -v185, v186, 1.0
	v_fmac_f32_e32 v186, v188, v186
	v_mul_f32_e32 v188, v187, v186
	v_fma_f32 v189, -v185, v188, v187
	v_fmac_f32_e32 v188, v189, v186
	v_fma_f32 v187, -v185, v188, v187
	v_div_fmas_f32 v187, v187, v186, v188
	v_div_fixup_f32 v182, v187, v182, 2.0
	v_lshlrev_b32_e32 v191, 6, v190
	v_and_b32_e32 v191, 0x1c0, v191
	v_lshrrev_b32_e32 v190, 1, v190
	v_and_b32_e32 v190, 0x3c, v190
	v_or_b32_e32 v191, v191, v190
	v_sub_f32_e32 v182, 1.0, v182
	v_add_f32_e32 v182, 1.0, v182
	v_mul_f32_e32 v182, v184, v182
	v_mul_f32_e32 v182, v155, v182
	v_mul_f32_e32 v182, v153, v182
	s_and_saveexec_b64 s[92:93], s[16:17]
	global_store_dword v191, v182, s[36:37]
	s_mov_b64 exec, s[92:93]
	s_add_i32 s12, s12, 24
	s_cmp_lt_u32 s12, s11
	s_cbranch_scc1 .Lp11a_chunk
.Lp11a_next:
	s_add_i32 s6, s6, s4
	s_cmp_lt_i32 s6, s22
	s_cbranch_scc1 .Lp11a_tok
	s_branch .Lp11a_done
.Lp11a_empty:
	s_lshl_b32 s0, s7, 9
	s_add_u32 s8, s38, s0
	s_addc_u32 s9, s39, 0
	global_load_dword v10, v0, s[8:9]
	global_load_dword v11, v0, s[8:9] offset:256
	s_add_u32 s8, s42, s0
	s_addc_u32 s9, s43, 0
	global_load_dword v12, v0, s[8:9]
	global_load_dword v13, v0, s[8:9] offset:256
	s_lshl_b32 s0, s7, 10
	s_add_u32 s8, s62, s0
	s_addc_u32 s9, s63, 0
	global_load_dwordx4 v[32:35], v1, s[8:9]
	global_load_dwordx4 v[36:39], v1, s[8:9] offset:256
	global_load_dwordx4 v[40:43], v1, s[8:9] offset:512
	global_load_dwordx4 v[44:47], v1, s[8:9] offset:768
	s_lshl_b32 s0, s7, 2
	s_add_u32 s8, s30, s0
	s_addc_u32 s9, s31, 0
	s_load_dword s15, s[8:9], 0x0
	s_waitcnt vmcnt(0)
	s_branch .Lp11a_next
.Lp11a_done:
	s_waitcnt vmcnt(0) lgkmcnt(0)
